# scan2 loader waves: once-read operand/V chunk loads marked nt
# speedup vs baseline: 1.0062x; 1.0051x over previous
; #define LAS __attribute__((address_space(3)))
; __device__ __forceinline__ void sc2_issue(u32x4 (&R)[SG_NL], const unsigned char* ops, const unsigned char* sv, int grp, int lt) {
;     if (grp > 63) grp = 63;
;     const unsigned char* og = ops + (size_t)grp * SG_OPS; const unsigned char* vg = sv + (size_t)grp * (SG * 2048);
; #pragma unroll
;     for (int i = 0; i < SG_NL; ++i) { int idx = lt + 256 * i; idx = idx < SG_N16 ? idx : SG_N16 - 1;
;         const unsigned char* p = (idx < SG_OPS / 16) ? (og + (size_t)idx * 16) : (vg + (size_t)(idx - SG_OPS / 16) * 16); R[i] = *(const u32x4*)p; }
; }
; __device__ __forceinline__ void sc2_commit(const u32x4 (&R)[SG_NL], LAS unsigned char* buf, int lt) {
; #pragma unroll
;     for (int i = 0; i < SG_NL; ++i) { int idx = lt + 256 * i; idx = idx < SG_N16 ? idx : SG_N16 - 1; *(LAS u32x4*)(buf + idx * 16) = R[i]; }
; }
; __device__ __forceinline__ void scan2_phase(LAS unsigned char* lds, const unsigned char* OPS, const bf16* SV, bf16* mix, int bid, int G, int tid) {
;     const int wid = __builtin_amdgcn_readfirstlane(tid >> 6), lane = tid & 63, lt = tid & 255; const bool loader = wid >= 4;
;     LAS unsigned char* buf0 = lds; LAS unsigned char* buf1 = lds + SG_BYTES;
;     for (int bh = bid; bh < 64; bh += G) { const int b = bh >> 4, h = bh & 15;
;         const unsigned char* ops = OPS + (size_t)bh * 256 * PCI_BYTES; const unsigned char* sv = (const unsigned char*)(SV + (size_t)bh * SEQ * 64);
;         bf16* ybase = mix + (size_t)(b * SEQ) * D + 1024 + h * 64 + (wid & 3) * 16 + (lane & 15);
;         u32x4 ra[SG_NL], rb[SG_NL]; f32x4 Z[4];
; #pragma unroll
;         for (int kt = 0; kt < 4; ++kt) Z[kt] = (f32x4){0.f, 0.f, 0.f, 0.f};
;         if (loader) { sc2_issue(ra, ops, sv, 0, lt); sc2_issue(rb, ops, sv, 1, lt); sc2_commit(ra, buf0, lt); sc2_issue(ra, ops, sv, 2, lt); }
.LBB0_376:
	s_ashr_i32 s43, s42, 31
	s_mul_i32 s6, s42, 0x290000
	s_lshl_b64 s[0:1], s[42:43], 19
	v_readlane_b32 s30, v255, 5
	s_mul_hi_i32 s5, s42, 0x290000
	v_readlane_b32 s31, v255, 6
	s_add_u32 s56, s30, s6
	s_addc_u32 s57, s31, s5
	s_add_u32 s62, s80, s0
	s_addc_u32 s63, s81, s1
	s_andn2_b64 vcc, exec, s[34:35]
	v_add_u32_e32 v160, 0, v142
	s_cbranch_vccnz .LBB0_378
	s_waitcnt vmcnt(0)
	v_lshl_add_u64 v[0:1], s[56:57], 0, v[140:141]
	v_add_co_u32_e32 v2, vcc, 0x1000, v0
	s_add_u32 s0, s56, 0xa400
	s_nop 0
	v_addc_co_u32_e32 v3, vcc, 0, v1, vcc
	global_load_dwordx4 v[40:43], v[0:1], off nt
	global_load_dwordx4 v[44:47], v[2:3], off nt
	v_add_co_u32_e32 v2, vcc, 0x2000, v0
	s_addc_u32 s1, s57, 0
	s_nop 0
	v_addc_co_u32_e32 v3, vcc, 0, v1, vcc
	v_add_co_u32_e32 v4, vcc, 0x3000, v0
	v_lshl_add_u64 v[32:33], s[0:1], 0, v[140:141]
	s_nop 0
	v_addc_co_u32_e32 v5, vcc, 0, v1, vcc
	global_load_dwordx4 v[56:59], v[2:3], off nt
	global_load_dwordx4 v[64:67], v[4:5], off nt
	v_add_co_u32_e32 v2, vcc, s11, v0
	s_add_u32 s6, s62, 0x2000
	s_nop 0
	v_addc_co_u32_e32 v3, vcc, 0, v1, vcc
	v_add_co_u32_e32 v4, vcc, 0x5000, v0
	s_addc_u32 s7, s63, 0
	s_nop 0
	v_addc_co_u32_e32 v5, vcc, 0, v1, vcc
	global_load_dwordx4 v[68:71], v[2:3], off nt
	global_load_dwordx4 v[72:75], v[4:5], off nt
	v_add_co_u32_e32 v2, vcc, 0x6000, v0
	v_lshl_add_u64 v[54:55], s[6:7], 0, v[142:143]
	s_nop 0
	v_addc_co_u32_e32 v3, vcc, 0, v1, vcc
	v_add_co_u32_e32 v4, vcc, s17, v0
	v_lshl_add_u64 v[48:49], s[0:1], 0, v[146:147]
	s_nop 0
	v_addc_co_u32_e32 v5, vcc, 0, v1, vcc
	global_load_dwordx4 v[76:79], v[2:3], off nt
	global_load_dwordx4 v[80:83], v[4:5], off nt
	v_add_co_u32_e32 v2, vcc, s9, v0
	v_lshl_add_u64 v[50:51], s[6:7], 0, v[144:145]
	s_nop 0
	v_addc_co_u32_e32 v3, vcc, 0, v1, vcc
	v_add_co_u32_e32 v0, vcc, 0x9000, v0
	s_add_u32 s0, s56, 0x14800
	s_nop 0
	v_addc_co_u32_e32 v1, vcc, 0, v1, vcc
	global_load_dwordx4 v[84:87], v[2:3], off nt
	global_load_dwordx4 v[88:91], v[0:1], off nt
	v_lshl_add_u64 v[0:1], s[56:57], 0, v[146:147]
	v_lshl_add_u64 v[2:3], s[62:63], 0, v[144:145]
	v_cndmask_b32_e64 v1, v3, v1, s[38:39]
	v_cndmask_b32_e64 v0, v2, v0, s[38:39]
	v_lshl_add_u64 v[2:3], s[62:63], 0, v[142:143]
	global_load_dwordx4 v[92:95], v[0:1], off nt
	v_lshl_add_u64 v[0:1], s[62:63], 0, v[140:141]
	v_add_co_u32_e32 v2, vcc, s28, v2
	v_cndmask_b32_e64 v49, v51, v49, s[38:39]
	s_nop 0
	v_addc_co_u32_e32 v3, vcc, -1, v3, vcc
	global_load_dwordx4 v[98:101], v[0:1], off offset:3072 nt
	global_load_dwordx4 v[102:105], v[2:3], off nt
	v_add_co_u32_e32 v4, vcc, s55, v32
	v_cndmask_b32_e64 v48, v50, v48, s[38:39]
	s_nop 0
	v_addc_co_u32_e32 v5, vcc, 0, v33, vcc
	v_add_co_u32_e32 v8, vcc, s13, v32
	v_lshl_add_u64 v[52:53], s[6:7], 0, v[140:141]
	s_nop 0
	v_addc_co_u32_e32 v9, vcc, 0, v33, vcc
	v_add_co_u32_e32 v12, vcc, s54, v32
	s_addc_u32 s1, s57, 0
	s_nop 0
	v_addc_co_u32_e32 v13, vcc, 0, v33, vcc
	v_add_co_u32_e32 v16, vcc, s11, v32
	global_load_dwordx4 v[0:3], v[32:33], off nt
	s_nop 0
	global_load_dwordx4 v[4:7], v[4:5], off nt
	v_addc_co_u32_e32 v17, vcc, 0, v33, vcc
	v_add_co_u32_e32 v20, vcc, s14, v32
	global_load_dwordx4 v[8:11], v[8:9], off nt
	s_nop 0
	global_load_dwordx4 v[12:15], v[12:13], off nt
	v_addc_co_u32_e32 v21, vcc, 0, v33, vcc
	v_add_co_u32_e32 v24, vcc, s15, v32
	global_load_dwordx4 v[16:19], v[16:17], off nt
	s_nop 0
	global_load_dwordx4 v[20:23], v[20:21], off nt
	v_addc_co_u32_e32 v25, vcc, 0, v33, vcc
	v_add_co_u32_e32 v28, vcc, s17, v32
	s_add_u32 s6, s62, 0x4000
	s_nop 0
	v_addc_co_u32_e32 v29, vcc, 0, v33, vcc
	v_add_co_u32_e32 v34, vcc, s9, v32
	global_load_dwordx4 v[24:27], v[24:25], off nt
	s_nop 0
	global_load_dwordx4 v[28:31], v[28:29], off nt
	v_addc_co_u32_e32 v35, vcc, 0, v33, vcc
	v_add_co_u32_e32 v36, vcc, s19, v32
	s_addc_u32 s7, s63, 0
	s_nop 0
	v_addc_co_u32_e32 v37, vcc, 0, v33, vcc
	v_add_co_u32_e32 v60, vcc, s28, v54
	global_load_dwordx4 v[32:35], v[34:35], off nt
	s_nop 0
	global_load_dwordx4 v[36:39], v[36:37], off nt
	v_addc_co_u32_e32 v61, vcc, -1, v55, vcc
	global_load_dwordx4 v[48:51], v[48:49], off nt
	s_nop 0
	global_load_dwordx4 v[52:55], v[52:53], off offset:3072 nt
	s_nop 0
	global_load_dwordx4 v[60:63], v[60:61], off nt
	s_waitcnt vmcnt(0) lgkmcnt(0)
	ds_write_b128 v152, v[40:43]
	ds_write_b128 v152, v[44:47] offset:4096
	ds_write_b128 v152, v[56:59] offset:8192
	ds_write_b128 v152, v[64:67] offset:12288
	ds_write_b128 v152, v[68:71] offset:16384
	ds_write_b128 v152, v[72:75] offset:20480
	ds_write_b128 v152, v[76:79] offset:24576
	ds_write_b128 v152, v[80:83] offset:28672
	ds_write_b128 v152, v[84:87] offset:32768
	ds_write_b128 v152, v[88:91] offset:36864
	ds_write_b128 v152, v[92:95] offset:40960
	ds_write_b128 v152, v[98:101] offset:45056
	ds_write_b128 v160, v[102:105]
	v_lshl_add_u64 v[84:85], s[0:1], 0, v[140:141]
	v_add_co_u32_e32 v44, vcc, s55, v84
	v_lshl_add_u64 v[100:101], s[6:7], 0, v[142:143]
	s_nop 0
	v_addc_co_u32_e32 v45, vcc, 0, v85, vcc
	v_add_co_u32_e32 v56, vcc, s13, v84
	v_lshl_add_u64 v[92:93], s[0:1], 0, v[146:147]
	s_nop 0
	v_addc_co_u32_e32 v57, vcc, 0, v85, vcc
	v_add_co_u32_e32 v64, vcc, s54, v84
	v_lshl_add_u64 v[94:95], s[6:7], 0, v[144:145]
	s_nop 0
	v_addc_co_u32_e32 v65, vcc, 0, v85, vcc
	v_add_co_u32_e32 v68, vcc, s11, v84
	v_cndmask_b32_e64 v93, v95, v93, s[38:39]
	s_nop 0
	v_addc_co_u32_e32 v69, vcc, 0, v85, vcc
	v_add_co_u32_e32 v72, vcc, s14, v84
	v_cndmask_b32_e64 v92, v94, v92, s[38:39]
	s_nop 0
	v_addc_co_u32_e32 v73, vcc, 0, v85, vcc
	v_add_co_u32_e32 v76, vcc, s15, v84
	v_lshl_add_u64 v[98:99], s[6:7], 0, v[140:141]
	s_nop 0
	v_addc_co_u32_e32 v77, vcc, 0, v85, vcc
	v_add_co_u32_e32 v80, vcc, s17, v84
	global_load_dwordx4 v[40:43], v[84:85], off nt
	s_nop 0
	global_load_dwordx4 v[44:47], v[44:45], off nt
	v_addc_co_u32_e32 v81, vcc, 0, v85, vcc
	v_add_co_u32_e32 v86, vcc, s9, v84
	global_load_dwordx4 v[56:59], v[56:57], off nt
	s_nop 0
	global_load_dwordx4 v[64:67], v[64:65], off nt
	v_addc_co_u32_e32 v87, vcc, 0, v85, vcc
	v_add_co_u32_e32 v88, vcc, s19, v84
	global_load_dwordx4 v[68:71], v[68:69], off nt
	s_nop 0
	global_load_dwordx4 v[72:75], v[72:73], off nt
	v_addc_co_u32_e32 v89, vcc, 0, v85, vcc
	v_add_co_u32_e32 v104, vcc, 0xffff5c00, v100
	global_load_dwordx4 v[76:79], v[76:77], off nt
	s_nop 0
	global_load_dwordx4 v[80:83], v[80:81], off nt
	v_addc_co_u32_e32 v105, vcc, -1, v101, vcc
	global_load_dwordx4 v[84:87], v[86:87], off nt
	s_nop 0
	global_load_dwordx4 v[88:91], v[88:89], off nt
	s_nop 0
	global_load_dwordx4 v[92:95], v[92:93], off nt
	s_nop 0
	global_load_dwordx4 v[100:103], v[98:99], off offset:3072 nt
	s_nop 0
	global_load_dwordx4 v[104:107], v[104:105], off nt

; #define LAS __attribute__((address_space(3)))
; __device__ __forceinline__ void sc2_issue(u32x4 (&R)[SG_NL], const unsigned char* ops, const unsigned char* sv, int grp, int lt) {
;     if (grp > 63) grp = 63;
;     const unsigned char* og = ops + (size_t)grp * SG_OPS; const unsigned char* vg = sv + (size_t)grp * (SG * 2048);
; #pragma unroll
;     for (int i = 0; i < SG_NL; ++i) { int idx = lt + 256 * i; idx = idx < SG_N16 ? idx : SG_N16 - 1;
;         const unsigned char* p = (idx < SG_OPS / 16) ? (og + (size_t)idx * 16) : (vg + (size_t)(idx - SG_OPS / 16) * 16); R[i] = *(const u32x4*)p; }
; }
; __device__ __forceinline__ void sc2_commit(const u32x4 (&R)[SG_NL], LAS unsigned char* buf, int lt) {
; #pragma unroll
;     for (int i = 0; i < SG_NL; ++i) { int idx = lt + 256 * i; idx = idx < SG_N16 ? idx : SG_N16 - 1; *(LAS u32x4*)(buf + idx * 16) = R[i]; }
; }
; __device__ __forceinline__ void scan2_phase(LAS unsigned char* lds, const unsigned char* OPS, const bf16* SV, bf16* mix, int bid, int G, int tid) {
;     ...
;             else { sc2_commit(rb, buf1, lt); sc2_issue(rb, ops, sv, gi + 3, lt); }
.LBB0_383:
	s_and_b64 vcc, exec, s[0:1]
	s_cbranch_vccz .LBB0_385
	s_min_u32 s0, s5, 60
	s_add_i32 s6, s0, 3
	s_mul_i32 s0, s6, 0xa400
	s_add_u32 s0, s56, s0
	s_addc_u32 s1, s57, 0
	s_waitcnt vmcnt(0)
	ds_write_b128 v152, v[0:3] offset:50176
	ds_write_b128 v152, v[4:7] offset:54272
	ds_write_b128 v152, v[8:11] offset:58368
	ds_write_b128 v152, v[12:15] offset:62464
	ds_write_b128 v153, v[16:19] offset:16384
	ds_write_b128 v153, v[20:23] offset:20480
	ds_write_b128 v153, v[24:27] offset:24576
	ds_write_b128 v153, v[28:31] offset:28672
	ds_write_b128 v153, v[32:35] offset:32768
	ds_write_b128 v153, v[36:39] offset:36864
	ds_write_b128 v153, v[48:51] offset:40960
	ds_write_b128 v153, v[52:55] offset:45056
	ds_write_b128 v160, v[60:63] offset:50176
	v_lshl_add_u64 v[32:33], s[0:1], 0, v[140:141]
	v_add_co_u32_e32 v4, vcc, s55, v32
	s_lshl_b32 s6, s6, 13
	s_nop 0
	v_addc_co_u32_e32 v5, vcc, 0, v33, vcc
	v_add_co_u32_e32 v8, vcc, s13, v32
	s_add_u32 s6, s62, s6
	s_nop 0
	v_addc_co_u32_e32 v9, vcc, 0, v33, vcc
	v_add_co_u32_e32 v12, vcc, s54, v32
	s_addc_u32 s7, s63, 0
	s_nop 0
	v_addc_co_u32_e32 v13, vcc, 0, v33, vcc
	v_add_co_u32_e32 v16, vcc, s11, v32
	v_lshl_add_u64 v[54:55], s[6:7], 0, v[142:143]
	s_nop 0
	v_addc_co_u32_e32 v17, vcc, 0, v33, vcc
	v_add_co_u32_e32 v20, vcc, s14, v32
	v_lshl_add_u64 v[48:49], s[0:1], 0, v[146:147]
	s_nop 0
	v_addc_co_u32_e32 v21, vcc, 0, v33, vcc
	v_add_co_u32_e32 v24, vcc, s15, v32
	v_lshl_add_u64 v[50:51], s[6:7], 0, v[144:145]
	s_nop 0
	v_addc_co_u32_e32 v25, vcc, 0, v33, vcc
	v_add_co_u32_e32 v28, vcc, s17, v32
	v_cndmask_b32_e64 v49, v51, v49, s[38:39]
	s_nop 0
	v_addc_co_u32_e32 v29, vcc, 0, v33, vcc
	v_add_co_u32_e32 v34, vcc, s9, v32
	v_cndmask_b32_e64 v48, v50, v48, s[38:39]
	s_nop 0
	v_addc_co_u32_e32 v35, vcc, 0, v33, vcc
	v_add_co_u32_e32 v36, vcc, s19, v32
	v_lshl_add_u64 v[52:53], s[6:7], 0, v[140:141]
	s_nop 0
	v_addc_co_u32_e32 v37, vcc, 0, v33, vcc
	v_add_co_u32_e32 v60, vcc, 0xffff5c00, v54
	global_load_dwordx4 v[0:3], v[32:33], off nt
	s_nop 0
	global_load_dwordx4 v[4:7], v[4:5], off nt
	v_addc_co_u32_e32 v61, vcc, -1, v55, vcc
	global_load_dwordx4 v[8:11], v[8:9], off nt
	s_nop 0
	global_load_dwordx4 v[12:15], v[12:13], off nt
	s_nop 0
	global_load_dwordx4 v[16:19], v[16:17], off nt
	s_nop 0
	global_load_dwordx4 v[20:23], v[20:21], off nt
	s_nop 0
	global_load_dwordx4 v[24:27], v[24:25], off nt
	s_nop 0
	global_load_dwordx4 v[28:31], v[28:29], off nt
	s_nop 0
	global_load_dwordx4 v[32:35], v[34:35], off nt
	s_nop 0
	global_load_dwordx4 v[36:39], v[36:37], off nt
	s_nop 0
	global_load_dwordx4 v[48:51], v[48:49], off nt
	s_nop 0
	global_load_dwordx4 v[52:55], v[52:53], off offset:3072 nt
	s_nop 0
	global_load_dwordx4 v[60:63], v[60:61], off nt
	s_branch .LBB0_386

; #define LAS __attribute__((address_space(3)))
; __device__ __forceinline__ void sc2_issue(u32x4 (&R)[SG_NL], const unsigned char* ops, const unsigned char* sv, int grp, int lt) {
;     if (grp > 63) grp = 63;
;     const unsigned char* og = ops + (size_t)grp * SG_OPS; const unsigned char* vg = sv + (size_t)grp * (SG * 2048);
; #pragma unroll
;     for (int i = 0; i < SG_NL; ++i) { int idx = lt + 256 * i; idx = idx < SG_N16 ? idx : SG_N16 - 1;
;         const unsigned char* p = (idx < SG_OPS / 16) ? (og + (size_t)idx * 16) : (vg + (size_t)(idx - SG_OPS / 16) * 16); R[i] = *(const u32x4*)p; }
; }
; __device__ __forceinline__ void sc2_commit(const u32x4 (&R)[SG_NL], LAS unsigned char* buf, int lt) {
; #pragma unroll
;     for (int i = 0; i < SG_NL; ++i) { int idx = lt + 256 * i; idx = idx < SG_N16 ? idx : SG_N16 - 1; *(LAS u32x4*)(buf + idx * 16) = R[i]; }
; }
; __device__ __forceinline__ void scan2_phase(LAS unsigned char* lds, const unsigned char* OPS, const bf16* SV, bf16* mix, int bid, int G, int tid) {
;     ...
;             else { sc2_commit(ra, buf0, lt); sc2_issue(ra, ops, sv, gi + 4, lt); }
.LBB0_390:
	s_and_b64 vcc, exec, s[0:1]
	s_cbranch_vccz .LBB0_392
	s_min_u32 s0, s5, 59
	s_add_i32 s6, s0, 4
	s_mul_i32 s0, s6, 0xa400
	s_add_u32 s0, s56, s0
	s_addc_u32 s1, s57, 0
	s_waitcnt vmcnt(0)
	ds_write_b128 v152, v[40:43]
	ds_write_b128 v152, v[44:47] offset:4096
	ds_write_b128 v152, v[56:59] offset:8192
	ds_write_b128 v152, v[64:67] offset:12288
	ds_write_b128 v152, v[68:71] offset:16384
	ds_write_b128 v152, v[72:75] offset:20480
	ds_write_b128 v152, v[76:79] offset:24576
	ds_write_b128 v152, v[80:83] offset:28672
	ds_write_b128 v152, v[84:87] offset:32768
	ds_write_b128 v152, v[88:91] offset:36864
	ds_write_b128 v152, v[92:95] offset:40960
	ds_write_b128 v152, v[100:103] offset:45056
	ds_write_b128 v160, v[104:107]
	v_lshl_add_u64 v[84:85], s[0:1], 0, v[140:141]
	v_add_co_u32_e32 v44, vcc, s55, v84
	s_lshl_b32 s6, s6, 13
	s_nop 0
	v_addc_co_u32_e32 v45, vcc, 0, v85, vcc
	v_add_co_u32_e32 v56, vcc, s13, v84
	s_add_u32 s6, s62, s6
	s_nop 0
	v_addc_co_u32_e32 v57, vcc, 0, v85, vcc
	v_add_co_u32_e32 v64, vcc, s54, v84
	s_addc_u32 s7, s63, 0
	s_nop 0
	v_addc_co_u32_e32 v65, vcc, 0, v85, vcc
	v_add_co_u32_e32 v68, vcc, s11, v84
	v_lshl_add_u64 v[100:101], s[6:7], 0, v[142:143]
	s_nop 0
	v_addc_co_u32_e32 v69, vcc, 0, v85, vcc
	v_add_co_u32_e32 v72, vcc, s14, v84
	v_lshl_add_u64 v[92:93], s[0:1], 0, v[146:147]
	s_nop 0
	v_addc_co_u32_e32 v73, vcc, 0, v85, vcc
	v_add_co_u32_e32 v76, vcc, s15, v84
	v_lshl_add_u64 v[94:95], s[6:7], 0, v[144:145]
	s_nop 0
	v_addc_co_u32_e32 v77, vcc, 0, v85, vcc
	v_add_co_u32_e32 v80, vcc, s17, v84
	v_cndmask_b32_e64 v93, v95, v93, s[38:39]
	s_nop 0
	v_addc_co_u32_e32 v81, vcc, 0, v85, vcc
	v_add_co_u32_e32 v86, vcc, s9, v84
	v_cndmask_b32_e64 v92, v94, v92, s[38:39]
	s_nop 0
	v_addc_co_u32_e32 v87, vcc, 0, v85, vcc
	v_add_co_u32_e32 v88, vcc, s19, v84
	v_lshl_add_u64 v[98:99], s[6:7], 0, v[140:141]
	s_nop 0
	v_addc_co_u32_e32 v89, vcc, 0, v85, vcc
	v_add_co_u32_e32 v104, vcc, 0xffff5c00, v100
	global_load_dwordx4 v[40:43], v[84:85], off nt
	s_nop 0
	global_load_dwordx4 v[44:47], v[44:45], off nt
	v_addc_co_u32_e32 v105, vcc, -1, v101, vcc
	global_load_dwordx4 v[56:59], v[56:57], off nt
	s_nop 0
	global_load_dwordx4 v[64:67], v[64:65], off nt
	s_nop 0
	global_load_dwordx4 v[68:71], v[68:69], off nt
	s_nop 0
	global_load_dwordx4 v[72:75], v[72:73], off nt
	s_nop 0
	global_load_dwordx4 v[76:79], v[76:77], off nt
	s_nop 0
	global_load_dwordx4 v[80:83], v[80:81], off nt
	s_nop 0
	global_load_dwordx4 v[84:87], v[86:87], off nt
	s_nop 0
	global_load_dwordx4 v[88:91], v[88:89], off nt
	s_nop 0
	global_load_dwordx4 v[92:95], v[92:93], off nt
	s_nop 0
	global_load_dwordx4 v[100:103], v[98:99], off offset:3072 nt
	s_nop 0
	global_load_dwordx4 v[104:107], v[104:105], off nt
	s_branch .LBB0_393
